# split scan/attention with the attention workgroups starting ~30 us late instead of sleeping per tile
# baseline (speedup 1.0000x reference)
; __device__ __forceinline__ void phase_scan2(const Params& p, int l, LAS unsigned char* lds) {
;     ...
;         auto consume = [&](int c, LAS const unsigned char* sl) {
;             const bf16x8 s0 = __builtin_bit_cast(bf16x8, (u32x4){pk_bf16(ST[0][0], ST[0][1]), pk_bf16(ST[0][2], ST[0][3]), pk_bf16(ST[1][0], ST[1][1]), pk_bf16(ST[1][2], ST[1][3])});
;             const bf16x8 s1 = __builtin_bit_cast(bf16x8, (u32x4){pk_bf16(ST[2][0], ST[2][1]), pk_bf16(ST[2][2], ST[2][3]), pk_bf16(ST[3][0], ST[3][1]), pk_bf16(ST[3][2], ST[3][3])});
;             const bf16x8 at0 = *(LAS const bf16x8*)(sl + SC_AT + (fr * 32 + fq * 8) * 2), at1 = *(LAS const bf16x8*)(sl + SC_AT + ((16 + fr) * 32 + fq * 8) * 2);
;             const bf16x8 rt0 = *(LAS const bf16x8*)(sl + SC_RT + (fr * 32 + fq * 8) * 2), rt1 = *(LAS const bf16x8*)(sl + SC_RT + ((16 + fr) * 32 + fq * 8) * 2);
;             const int mo = (fr * 16 + 4 * fq) * 2;
;             const bf16x8 vf = frag4(sl + SC_VP + mo), akf = frag4(sl + SC_AK + mo), xf = frag4(sl + SC_X + mo), rbf = frag4(sl + SC_RB + mo), rkf = frag4(sl + SC_RK + mo);
;             const f32x4 z = (f32x4){0.f, 0.f, 0.f, 0.f};
;             f32x4 g = __builtin_amdgcn_mfma_f32_16x16x32_bf16(at0, s0, z, 0, 0, 0);
;             g = __builtin_amdgcn_mfma_f32_16x16x32_bf16(at1, s1, g, 0, 0, 0);
;             g = __builtin_amdgcn_mfma_f32_16x16x32_bf16(akf, vf, g, 0, 0, 0);
;             const f32x4 sa = __builtin_amdgcn_mfma_f32_16x16x32_bf16(xf, cfrag(g), z, 0, 0, 0);
;             const bf16x8 saf = cfrag(sa);
;             f32x4 y = __builtin_amdgcn_mfma_f32_16x16x32_bf16(rt0, s0, z, 0, 0, 0);
;             y = __builtin_amdgcn_mfma_f32_16x16x32_bf16(rt1, s1, y, 0, 0, 0);
;             y = __builtin_amdgcn_mfma_f32_16x16x32_bf16(rbf, saf, y, 0, 0, 0);
;             y = __builtin_amdgcn_mfma_f32_16x16x32_bf16(rkf, vf, y, 0, 0, 0);
; #pragma unroll
;             for (int jt = 0; jt < 4; ++jt) {
;                 const f32x4 wc = *(LAS const f32x4*)(sl + SC_WC + (16 * jt + 4 * fq) * 4);
;                 const bf16x8 bb = frag4(sl + SC_BBT + ((16 * jt + fr) * SC_BS + 4 * fq) * 2), kb = frag4(sl + SC_KBT + ((16 * jt + fr) * SC_BS + 4 * fq) * 2);
;                 f32x4 acc = ST[jt];
;                 acc = __builtin_amdgcn_mfma_f32_16x16x32_bf16(bb, saf, acc, 0, 0, 0);
;                 acc = __builtin_amdgcn_mfma_f32_16x16x32_bf16(kb, vf, acc, 0, 0, 0);
.Lsc_consumer:
	s_setprio 3
	v_and_b32_e32 v4, 7, v1
	s_lshr_b32 s1, s25, 2
	v_xor_b32_e32 v4, v4, v2
	s_mul_i32 s0, s1, 768
	v_lshlrev_b32_e32 v4, 4, v4
	v_and_b32_e32 v5, 3, v1
	v_lshl_add_u32 v163, v1, 7, v4
	v_lshrrev_b32_e32 v4, 2, v1
	v_add_u32_e32 v13, s0, v6
	v_lshl_add_u32 v4, v2, 2, v4
	s_add_u32 s53, s53, s1
	v_and_b32_e32 v165, 7, v4
	s_mul_i32 s0, s54, 4096
	v_xor_b32_e32 v165, v165, v5
	s_lshl_b32 s0, s0, 10
	v_lshlrev_b32_e32 v165, 4, v165
	s_lshl_b32 s14, s52, 7
	v_lshl_add_u32 v165, v4, 7, v165
	s_lshl_b32 s15, s53, 5
	s_add_u32 s0, s0, s14
	v_lshlrev_b32_e32 v164, 5, v2
	v_add_u32_e32 v165, 4096, v165
	v_lshlrev_b32_e32 v166, 12, v2
	s_add_u32 s0, s0, s15
	s_add_u32 s0, s0, 0x5000000
	v_mov_b32_e32 v8, 0
	v_mov_b32_e32 v116, 0
	v_mov_b32_e32 v9, 0
	v_mov_b32_e32 v117, 0
	v_mov_b32_e32 v10, 0
	v_mov_b32_e32 v118, 0
	v_mov_b32_e32 v11, 0
	v_mov_b32_e32 v119, 0
	v_mov_b32_e32 v16, 0
	v_mov_b32_e32 v120, 0
	v_mov_b32_e32 v17, 0
	v_mov_b32_e32 v121, 0
	v_mov_b32_e32 v18, 0
	v_mov_b32_e32 v122, 0
	v_mov_b32_e32 v19, 0
	v_mov_b32_e32 v123, 0
	v_mov_b32_e32 v20, 0
	v_mov_b32_e32 v124, 0
	v_mov_b32_e32 v21, 0
	v_mov_b32_e32 v125, 0
	v_mov_b32_e32 v22, 0
	v_mov_b32_e32 v126, 0
	v_mov_b32_e32 v23, 0
	v_mov_b32_e32 v127, 0
	v_mov_b32_e32 v24, 0
	v_mov_b32_e32 v128, 0
	v_mov_b32_e32 v25, 0
	v_mov_b32_e32 v129, 0
	v_mov_b32_e32 v26, 0
	v_mov_b32_e32 v130, 0
	v_mov_b32_e32 v27, 0
	v_mov_b32_e32 v131, 0
	v_xor_b32_e32 v169, 64, v163
	v_add_u32_e32 v164, 10752, v164
	v_xor_b32_e32 v170, 64, v165
	v_lshl_add_u32 v166, v1, 1, v166
	s_add_u32 s48, s74, s0
	s_addc_u32 s49, s75, 0
	s_mov_b32 s42, 0
	s_mov_b32 s58, 0
	s_mov_b32 s56, 0
	s_branch .Lsc_c_bar
.Lsc_c_loop:
	s_mov_b32 s57, s56
	s_cmp_ge_u32 s58, 256
	s_cbranch_scc1 .Lsc_c_itend
	v_add_u32_e32 v82, s57, v163
	v_add_u32_e32 v171, s57, v169
	ds_read_b128 v[36:39], v82 offset:0
	ds_read_b128 v[44:47], v82 offset:2048
	v_add_u32_e32 v160, s57, v13
	ds_read_b128 v[40:43], v171 offset:0
	v_add_u32_e32 v168, s57, v7
	ds_read_b128 v[48:51], v171 offset:2048
	ds_read_b64 v[60:61], v160 offset:10240
	ds_read_b64_tr_b16 v[14:15], v168 offset:8192
	ds_read_b64_tr_b16 v[52:53], v168 offset:8704
	v_add_u32_e32 v162, s57, v165
	ds_read_b64_tr_b16 v[56:57], v168 offset:9728
	ds_read_b64_tr_b16 v[58:59], v168 offset:9216
	v_add_u32_e32 v172, s57, v170
	ds_read_b64_tr_b16 v[88:89], v162 offset:2048
	ds_read_b64_tr_b16 v[92:93], v162 offset:2056
	v_add_u32_e32 v161, s57, v164
	ds_read_b64_tr_b16 v[96:97], v172 offset:2048
	v_cvt_pk_bf16_f32 v28, v8, v9
	v_cvt_pk_bf16_f32 v29, v10, v11
	v_cvt_pk_bf16_f32 v30, v16, v17
	v_cvt_pk_bf16_f32 v31, v18, v19
	v_cvt_pk_bf16_f32 v32, v20, v21
	v_cvt_pk_bf16_f32 v33, v22, v23
	v_cvt_pk_bf16_f32 v34, v24, v25
	v_cvt_pk_bf16_f32 v35, v26, v27
	ds_read_b64_tr_b16 v[100:101], v172 offset:2056
	s_waitcnt lgkmcnt(12)
	v_mfma_f32_16x16x32_bf16 v[104:107], v[36:39], v[28:31], 0
	ds_read_b128 v[36:39], v82 offset:11520
	s_waitcnt lgkmcnt(12)
	v_mfma_f32_16x16x32_bf16 v[112:115], v[44:47], v[28:31], 0
	ds_read_b128 v[44:47], v82 offset:13568
	s_waitcnt lgkmcnt(12)
	v_mfma_f32_16x16x32_bf16 v[104:107], v[40:43], v[32:35], v[104:107]
	ds_read_b128 v[40:43], v171 offset:11520
	s_waitcnt lgkmcnt(12)
	v_mfma_f32_16x16x32_bf16 v[112:115], v[48:51], v[32:35], v[112:115]
	ds_read_b128 v[48:51], v171 offset:13568
	s_waitcnt lgkmcnt(11)
	s_nop 0
	v_mfma_f32_16x16x16_bf16 v[104:107], v[14:15], v[60:61], v[104:107]
	ds_read_b64_tr_b16 v[90:91], v162 offset:0
	ds_read_b64_tr_b16 v[94:95], v162 offset:8
	ds_read_b64_tr_b16 v[98:99], v172 offset:0
	ds_read_b64_tr_b16 v[102:103], v172 offset:8
	s_nop 3
	v_cvt_pk_bf16_f32 v54, v104, v105
	v_cvt_pk_bf16_f32 v55, v106, v107
	s_waitcnt lgkmcnt(14)
	s_nop 0
	v_mfma_f32_16x16x16_bf16 v[108:111], v[52:53], v[54:55], 0
	s_nop 7
	v_cvt_pk_bf16_f32 v62, v108, v109
	v_cvt_pk_bf16_f32 v63, v110, v111
	s_waitcnt lgkmcnt(0)
	s_nop 0
	v_mfma_f32_16x16x32_bf16 v[112:115], v[56:59], v[60:63], v[112:115]
	v_mfma_f32_16x16x32_bf16 v[8:11], v[88:91], v[60:63], v[8:11]
	v_mfma_f32_16x16x32_bf16 v[16:19], v[92:95], v[60:63], v[16:19]
	v_mfma_f32_16x16x32_bf16 v[20:23], v[96:99], v[60:63], v[20:23]
	v_mfma_f32_16x16x32_bf16 v[24:27], v[100:103], v[60:63], v[24:27]
	ds_read_b128 v[64:67], v161 offset:0
	ds_read_b128 v[68:71], v161 offset:16
	ds_read_b128 v[72:75], v161 offset:128
	ds_read_b128 v[84:87], v161 offset:144
	v_cvt_pk_bf16_f32 v167, v112, v112
	ds_read_b64 v[60:61], v160 offset:21760
	global_store_short v166, v167, s[48:49] offset:0
	v_cvt_pk_bf16_f32 v167, v113, v113
	global_store_short v166, v167, s[48:49] offset:1024
	v_cvt_pk_bf16_f32 v167, v114, v114
	global_store_short v166, v167, s[48:49] offset:2048
	v_cvt_pk_bf16_f32 v167, v115, v115
	global_store_short v166, v167, s[48:49] offset:3072
	s_waitcnt lgkmcnt(1)
	s_add_u32 s58, s58, 1
	s_add_u32 s48, s48, 0x4000
	s_addc_u32 s49, s49, 0
	v_pk_mul_f32 v[8:9], v[8:9], v[64:65]
	v_pk_mul_f32 v[10:11], v[10:11], v[66:67]
	v_pk_mul_f32 v[16:17], v[16:17], v[68:69]
	v_pk_mul_f32 v[18:19], v[18:19], v[70:71]
	v_pk_mul_f32 v[20:21], v[20:21], v[72:73]
	v_pk_mul_f32 v[22:23], v[22:23], v[74:75]
	v_pk_mul_f32 v[24:25], v[24:25], v[84:85]
	v_pk_mul_f32 v[26:27], v[26:27], v[86:87]
	s_add_u32 s57, s57, 11520
	s_cmp_ge_u32 s58, 256
	s_cbranch_scc1 .Lsc_c_itend
; __device__ __forceinline__ void phase_scan2(const Params& p, int l, LAS unsigned char* lds) {
;     ...
;         auto consume = [&](int c, LAS const unsigned char* sl) {
;             const bf16x8 s0 = __builtin_bit_cast(bf16x8, (u32x4){pk_bf16(ST[0][0], ST[0][1]), pk_bf16(ST[0][2], ST[0][3]), pk_bf16(ST[1][0], ST[1][1]), pk_bf16(ST[1][2], ST[1][3])});
;             const bf16x8 s1 = __builtin_bit_cast(bf16x8, (u32x4){pk_bf16(ST[2][0], ST[2][1]), pk_bf16(ST[2][2], ST[2][3]), pk_bf16(ST[3][0], ST[3][1]), pk_bf16(ST[3][2], ST[3][3])});
;             const bf16x8 at0 = *(LAS const bf16x8*)(sl + SC_AT + (fr * 32 + fq * 8) * 2), at1 = *(LAS const bf16x8*)(sl + SC_AT + ((16 + fr) * 32 + fq * 8) * 2);
;             const bf16x8 rt0 = *(LAS const bf16x8*)(sl + SC_RT + (fr * 32 + fq * 8) * 2), rt1 = *(LAS const bf16x8*)(sl + SC_RT + ((16 + fr) * 32 + fq * 8) * 2);
;             const int mo = (fr * 16 + 4 * fq) * 2;
;             const bf16x8 vf = frag4(sl + SC_VP + mo), akf = frag4(sl + SC_AK + mo), xf = frag4(sl + SC_X + mo), rbf = frag4(sl + SC_RB + mo), rkf = frag4(sl + SC_RK + mo);
;             const f32x4 z = (f32x4){0.f, 0.f, 0.f, 0.f};
;             f32x4 g = __builtin_amdgcn_mfma_f32_16x16x32_bf16(at0, s0, z, 0, 0, 0);
;             g = __builtin_amdgcn_mfma_f32_16x16x32_bf16(at1, s1, g, 0, 0, 0);
;             g = __builtin_amdgcn_mfma_f32_16x16x32_bf16(akf, vf, g, 0, 0, 0);
;             const f32x4 sa = __builtin_amdgcn_mfma_f32_16x16x32_bf16(xf, cfrag(g), z, 0, 0, 0);
;             const bf16x8 saf = cfrag(sa);
;             f32x4 y = __builtin_amdgcn_mfma_f32_16x16x32_bf16(rt0, s0, z, 0, 0, 0);
;             y = __builtin_amdgcn_mfma_f32_16x16x32_bf16(rt1, s1, y, 0, 0, 0);
;             y = __builtin_amdgcn_mfma_f32_16x16x32_bf16(rbf, saf, y, 0, 0, 0);
;             y = __builtin_amdgcn_mfma_f32_16x16x32_bf16(rkf, vf, y, 0, 0, 0);
; #pragma unroll
;             for (int jt = 0; jt < 4; ++jt) {
;                 const f32x4 wc = *(LAS const f32x4*)(sl + SC_WC + (16 * jt + 4 * fq) * 4);
;                 const bf16x8 bb = frag4(sl + SC_BBT + ((16 * jt + fr) * SC_BS + 4 * fq) * 2), kb = frag4(sl + SC_KBT + ((16 * jt + fr) * SC_BS + 4 * fq) * 2);
;                 f32x4 acc = ST[jt];
;                 acc = __builtin_amdgcn_mfma_f32_16x16x32_bf16(bb, saf, acc, 0, 0, 0);
;                 acc = __builtin_amdgcn_mfma_f32_16x16x32_bf16(kb, vf, acc, 0, 0, 0);
	v_add_u32_e32 v168, s57, v7
	v_add_u32_e32 v162, s57, v165
	ds_read_b64_tr_b16 v[14:15], v168 offset:8192
	ds_read_b64_tr_b16 v[52:53], v168 offset:8704
	ds_read_b64_tr_b16 v[56:57], v168 offset:9728
	ds_read_b64_tr_b16 v[58:59], v168 offset:9216
	v_add_u32_e32 v172, s57, v170
	ds_read_b64_tr_b16 v[88:89], v162 offset:2048
	ds_read_b64_tr_b16 v[92:93], v162 offset:2056
	v_add_u32_e32 v82, s57, v163
	v_add_u32_e32 v160, s57, v13
	v_add_u32_e32 v161, s57, v164
	v_add_u32_e32 v171, s57, v169
	ds_read_b64_tr_b16 v[96:97], v172 offset:2048
	v_cvt_pk_bf16_f32 v28, v8, v9
	v_cvt_pk_bf16_f32 v29, v10, v11
	v_cvt_pk_bf16_f32 v30, v16, v17
	v_cvt_pk_bf16_f32 v31, v18, v19
	v_cvt_pk_bf16_f32 v32, v20, v21
	v_cvt_pk_bf16_f32 v33, v22, v23
	v_cvt_pk_bf16_f32 v34, v24, v25
	v_cvt_pk_bf16_f32 v35, v26, v27
	ds_read_b64_tr_b16 v[100:101], v172 offset:2056
	s_waitcnt lgkmcnt(12)
	v_mfma_f32_16x16x32_bf16 v[104:107], v[36:39], v[28:31], 0
	ds_read_b128 v[36:39], v82 offset:11520
	s_waitcnt lgkmcnt(12)
	v_mfma_f32_16x16x32_bf16 v[112:115], v[44:47], v[28:31], 0
	ds_read_b128 v[44:47], v82 offset:13568
	s_waitcnt lgkmcnt(12)
	v_mfma_f32_16x16x32_bf16 v[104:107], v[40:43], v[32:35], v[104:107]
	ds_read_b128 v[40:43], v171 offset:11520
	s_waitcnt lgkmcnt(12)
	v_mfma_f32_16x16x32_bf16 v[112:115], v[48:51], v[32:35], v[112:115]
	ds_read_b128 v[48:51], v171 offset:13568
	s_waitcnt lgkmcnt(11)
	s_nop 0
	v_mfma_f32_16x16x16_bf16 v[104:107], v[14:15], v[60:61], v[104:107]
	ds_read_b64_tr_b16 v[90:91], v162 offset:0
	ds_read_b64_tr_b16 v[94:95], v162 offset:8
	ds_read_b64_tr_b16 v[98:99], v172 offset:0
	ds_read_b64_tr_b16 v[102:103], v172 offset:8
	s_nop 3
	v_cvt_pk_bf16_f32 v54, v104, v105
	v_cvt_pk_bf16_f32 v55, v106, v107
	s_waitcnt lgkmcnt(14)
	s_nop 0
	v_mfma_f32_16x16x16_bf16 v[108:111], v[52:53], v[54:55], 0
	s_nop 7
	v_cvt_pk_bf16_f32 v62, v108, v109
	v_cvt_pk_bf16_f32 v63, v110, v111
	s_waitcnt lgkmcnt(0)
	s_nop 0
	v_mfma_f32_16x16x32_bf16 v[112:115], v[56:59], v[60:63], v[112:115]
	v_mfma_f32_16x16x32_bf16 v[8:11], v[88:91], v[60:63], v[8:11]
	v_mfma_f32_16x16x32_bf16 v[16:19], v[92:95], v[60:63], v[16:19]
	v_mfma_f32_16x16x32_bf16 v[20:23], v[96:99], v[60:63], v[20:23]
	v_mfma_f32_16x16x32_bf16 v[24:27], v[100:103], v[60:63], v[24:27]
	ds_read_b128 v[64:67], v161 offset:0
	ds_read_b128 v[68:71], v161 offset:16
	ds_read_b128 v[72:75], v161 offset:128
	ds_read_b128 v[84:87], v161 offset:144
	v_cvt_pk_bf16_f32 v167, v112, v112
	ds_read_b64 v[60:61], v160 offset:21760
	global_store_short v166, v167, s[48:49] offset:0
	v_cvt_pk_bf16_f32 v167, v113, v113
	global_store_short v166, v167, s[48:49] offset:1024
	v_cvt_pk_bf16_f32 v167, v114, v114
	global_store_short v166, v167, s[48:49] offset:2048
	v_cvt_pk_bf16_f32 v167, v115, v115
	global_store_short v166, v167, s[48:49] offset:3072
	s_waitcnt lgkmcnt(1)
	s_add_u32 s58, s58, 1
	s_add_u32 s48, s48, 0x4000
	s_addc_u32 s49, s49, 0
	v_pk_mul_f32 v[8:9], v[8:9], v[64:65]
	v_pk_mul_f32 v[10:11], v[10:11], v[66:67]
	v_pk_mul_f32 v[16:17], v[16:17], v[68:69]
	v_pk_mul_f32 v[18:19], v[18:19], v[70:71]
	v_pk_mul_f32 v[20:21], v[20:21], v[72:73]
	v_pk_mul_f32 v[22:23], v[22:23], v[74:75]
	v_pk_mul_f32 v[24:25], v[24:25], v[84:85]
	v_pk_mul_f32 v[26:27], v[26:27], v[86:87]
	s_add_u32 s57, s57, 11520
	s_cmp_ge_u32 s58, 256
	s_cbranch_scc1 .Lsc_c_itend
	v_add_u32_e32 v168, s57, v7
	v_add_u32_e32 v162, s57, v165
	ds_read_b64_tr_b16 v[14:15], v168 offset:8192
	ds_read_b64_tr_b16 v[52:53], v168 offset:8704
	ds_read_b64_tr_b16 v[56:57], v168 offset:9728
	ds_read_b64_tr_b16 v[58:59], v168 offset:9216
	v_add_u32_e32 v172, s57, v170
	ds_read_b64_tr_b16 v[88:89], v162 offset:2048
	ds_read_b64_tr_b16 v[92:93], v162 offset:2056
	v_add_u32_e32 v82, s57, v163
	v_add_u32_e32 v160, s57, v13
	v_add_u32_e32 v161, s57, v164
	v_add_u32_e32 v171, s57, v169
	ds_read_b64_tr_b16 v[96:97], v172 offset:2048
	v_cvt_pk_bf16_f32 v28, v8, v9
	v_cvt_pk_bf16_f32 v29, v10, v11
	v_cvt_pk_bf16_f32 v30, v16, v17
	v_cvt_pk_bf16_f32 v31, v18, v19
	v_cvt_pk_bf16_f32 v32, v20, v21
	v_cvt_pk_bf16_f32 v33, v22, v23
	v_cvt_pk_bf16_f32 v34, v24, v25
	v_cvt_pk_bf16_f32 v35, v26, v27
	ds_read_b64_tr_b16 v[100:101], v172 offset:2056
	s_waitcnt lgkmcnt(12)
	v_mfma_f32_16x16x32_bf16 v[104:107], v[36:39], v[28:31], 0
	ds_read_b128 v[36:39], v82 offset:11520
	s_waitcnt lgkmcnt(12)
	v_mfma_f32_16x16x32_bf16 v[112:115], v[44:47], v[28:31], 0
	ds_read_b128 v[44:47], v82 offset:13568
	s_waitcnt lgkmcnt(12)
	v_mfma_f32_16x16x32_bf16 v[104:107], v[40:43], v[32:35], v[104:107]
	ds_read_b128 v[40:43], v171 offset:11520
	s_waitcnt lgkmcnt(12)
	v_mfma_f32_16x16x32_bf16 v[112:115], v[48:51], v[32:35], v[112:115]
	ds_read_b128 v[48:51], v171 offset:13568
	s_waitcnt lgkmcnt(11)
	s_nop 0
	v_mfma_f32_16x16x16_bf16 v[104:107], v[14:15], v[60:61], v[104:107]
	ds_read_b64_tr_b16 v[90:91], v162 offset:0
	ds_read_b64_tr_b16 v[94:95], v162 offset:8
	ds_read_b64_tr_b16 v[98:99], v172 offset:0
	ds_read_b64_tr_b16 v[102:103], v172 offset:8
	s_nop 3
	v_cvt_pk_bf16_f32 v54, v104, v105
	v_cvt_pk_bf16_f32 v55, v106, v107
	s_waitcnt lgkmcnt(14)
	s_nop 0
	v_mfma_f32_16x16x16_bf16 v[108:111], v[52:53], v[54:55], 0
	s_nop 7
	v_cvt_pk_bf16_f32 v62, v108, v109
	v_cvt_pk_bf16_f32 v63, v110, v111
	s_waitcnt lgkmcnt(0)
	s_nop 0
	v_mfma_f32_16x16x32_bf16 v[112:115], v[56:59], v[60:63], v[112:115]
	v_mfma_f32_16x16x32_bf16 v[8:11], v[88:91], v[60:63], v[8:11]
	v_mfma_f32_16x16x32_bf16 v[16:19], v[92:95], v[60:63], v[16:19]
	v_mfma_f32_16x16x32_bf16 v[20:23], v[96:99], v[60:63], v[20:23]
	v_mfma_f32_16x16x32_bf16 v[24:27], v[100:103], v[60:63], v[24:27]
	ds_read_b128 v[64:67], v161 offset:0
	ds_read_b128 v[68:71], v161 offset:16
	ds_read_b128 v[72:75], v161 offset:128
	ds_read_b128 v[84:87], v161 offset:144
	v_cvt_pk_bf16_f32 v167, v112, v112
	ds_read_b64 v[60:61], v160 offset:21760
	global_store_short v166, v167, s[48:49] offset:0
	v_cvt_pk_bf16_f32 v167, v113, v113
	global_store_short v166, v167, s[48:49] offset:1024
	v_cvt_pk_bf16_f32 v167, v114, v114
	global_store_short v166, v167, s[48:49] offset:2048
	v_cvt_pk_bf16_f32 v167, v115, v115
	global_store_short v166, v167, s[48:49] offset:3072
	s_waitcnt lgkmcnt(1)
	s_add_u32 s58, s58, 1
	s_add_u32 s48, s48, 0x4000
	s_addc_u32 s49, s49, 0
	v_pk_mul_f32 v[8:9], v[8:9], v[64:65]
	v_pk_mul_f32 v[10:11], v[10:11], v[66:67]
	v_pk_mul_f32 v[16:17], v[16:17], v[68:69]
	v_pk_mul_f32 v[18:19], v[18:19], v[70:71]
	v_pk_mul_f32 v[20:21], v[20:21], v[72:73]
	v_pk_mul_f32 v[22:23], v[22:23], v[74:75]
	v_pk_mul_f32 v[24:25], v[24:25], v[84:85]
	v_pk_mul_f32 v[26:27], v[26:27], v[86:87]
	s_add_u32 s57, s57, 11520
	s_cmp_ge_u32 s58, 256
	s_cbranch_scc1 .Lsc_c_itend
; __device__ __forceinline__ void phase_scan2(const Params& p, int l, LAS unsigned char* lds) {
;     ...
;         auto consume = [&](int c, LAS const unsigned char* sl) {
;             const bf16x8 s0 = __builtin_bit_cast(bf16x8, (u32x4){pk_bf16(ST[0][0], ST[0][1]), pk_bf16(ST[0][2], ST[0][3]), pk_bf16(ST[1][0], ST[1][1]), pk_bf16(ST[1][2], ST[1][3])});
;             const bf16x8 s1 = __builtin_bit_cast(bf16x8, (u32x4){pk_bf16(ST[2][0], ST[2][1]), pk_bf16(ST[2][2], ST[2][3]), pk_bf16(ST[3][0], ST[3][1]), pk_bf16(ST[3][2], ST[3][3])});
;             const bf16x8 at0 = *(LAS const bf16x8*)(sl + SC_AT + (fr * 32 + fq * 8) * 2), at1 = *(LAS const bf16x8*)(sl + SC_AT + ((16 + fr) * 32 + fq * 8) * 2);
;             const bf16x8 rt0 = *(LAS const bf16x8*)(sl + SC_RT + (fr * 32 + fq * 8) * 2), rt1 = *(LAS const bf16x8*)(sl + SC_RT + ((16 + fr) * 32 + fq * 8) * 2);
;             const int mo = (fr * 16 + 4 * fq) * 2;
;             const bf16x8 vf = frag4(sl + SC_VP + mo), akf = frag4(sl + SC_AK + mo), xf = frag4(sl + SC_X + mo), rbf = frag4(sl + SC_RB + mo), rkf = frag4(sl + SC_RK + mo);
;             const f32x4 z = (f32x4){0.f, 0.f, 0.f, 0.f};
;             f32x4 g = __builtin_amdgcn_mfma_f32_16x16x32_bf16(at0, s0, z, 0, 0, 0);
;             g = __builtin_amdgcn_mfma_f32_16x16x32_bf16(at1, s1, g, 0, 0, 0);
;             g = __builtin_amdgcn_mfma_f32_16x16x32_bf16(akf, vf, g, 0, 0, 0);
;             const f32x4 sa = __builtin_amdgcn_mfma_f32_16x16x32_bf16(xf, cfrag(g), z, 0, 0, 0);
;             const bf16x8 saf = cfrag(sa);
;             f32x4 y = __builtin_amdgcn_mfma_f32_16x16x32_bf16(rt0, s0, z, 0, 0, 0);
;             y = __builtin_amdgcn_mfma_f32_16x16x32_bf16(rt1, s1, y, 0, 0, 0);
;             y = __builtin_amdgcn_mfma_f32_16x16x32_bf16(rbf, saf, y, 0, 0, 0);
;             y = __builtin_amdgcn_mfma_f32_16x16x32_bf16(rkf, vf, y, 0, 0, 0);
; #pragma unroll
;             for (int jt = 0; jt < 4; ++jt) {
;                 const f32x4 wc = *(LAS const f32x4*)(sl + SC_WC + (16 * jt + 4 * fq) * 4);
;                 const bf16x8 bb = frag4(sl + SC_BBT + ((16 * jt + fr) * SC_BS + 4 * fq) * 2), kb = frag4(sl + SC_KBT + ((16 * jt + fr) * SC_BS + 4 * fq) * 2);
;                 f32x4 acc = ST[jt];
;                 acc = __builtin_amdgcn_mfma_f32_16x16x32_bf16(bb, saf, acc, 0, 0, 0);
;                 acc = __builtin_amdgcn_mfma_f32_16x16x32_bf16(kb, vf, acc, 0, 0, 0);
	v_add_u32_e32 v168, s57, v7
	v_add_u32_e32 v162, s57, v165
	ds_read_b64_tr_b16 v[14:15], v168 offset:8192
	ds_read_b64_tr_b16 v[52:53], v168 offset:8704
	ds_read_b64_tr_b16 v[56:57], v168 offset:9728
	ds_read_b64_tr_b16 v[58:59], v168 offset:9216
	v_add_u32_e32 v172, s57, v170
	ds_read_b64_tr_b16 v[88:89], v162 offset:2048
	ds_read_b64_tr_b16 v[92:93], v162 offset:2056
	v_add_u32_e32 v82, s57, v163
	v_add_u32_e32 v160, s57, v13
	v_add_u32_e32 v161, s57, v164
	v_add_u32_e32 v171, s57, v169
	ds_read_b64_tr_b16 v[96:97], v172 offset:2048
	v_cvt_pk_bf16_f32 v28, v8, v9
	v_cvt_pk_bf16_f32 v29, v10, v11
	v_cvt_pk_bf16_f32 v30, v16, v17
	v_cvt_pk_bf16_f32 v31, v18, v19
	v_cvt_pk_bf16_f32 v32, v20, v21
	v_cvt_pk_bf16_f32 v33, v22, v23
	v_cvt_pk_bf16_f32 v34, v24, v25
	v_cvt_pk_bf16_f32 v35, v26, v27
	ds_read_b64_tr_b16 v[100:101], v172 offset:2056
	s_waitcnt lgkmcnt(12)
	v_mfma_f32_16x16x32_bf16 v[104:107], v[36:39], v[28:31], 0
	ds_read_b128 v[36:39], v82 offset:11520
	s_waitcnt lgkmcnt(12)
	v_mfma_f32_16x16x32_bf16 v[112:115], v[44:47], v[28:31], 0
	ds_read_b128 v[44:47], v82 offset:13568
	s_waitcnt lgkmcnt(12)
	v_mfma_f32_16x16x32_bf16 v[104:107], v[40:43], v[32:35], v[104:107]
	ds_read_b128 v[40:43], v171 offset:11520
	s_waitcnt lgkmcnt(12)
	v_mfma_f32_16x16x32_bf16 v[112:115], v[48:51], v[32:35], v[112:115]
	ds_read_b128 v[48:51], v171 offset:13568
	s_waitcnt lgkmcnt(11)
	s_nop 0
	v_mfma_f32_16x16x16_bf16 v[104:107], v[14:15], v[60:61], v[104:107]
	ds_read_b64_tr_b16 v[90:91], v162 offset:0
	ds_read_b64_tr_b16 v[94:95], v162 offset:8
	ds_read_b64_tr_b16 v[98:99], v172 offset:0
	ds_read_b64_tr_b16 v[102:103], v172 offset:8
	s_nop 3
	v_cvt_pk_bf16_f32 v54, v104, v105
	v_cvt_pk_bf16_f32 v55, v106, v107
	s_waitcnt lgkmcnt(14)
	s_nop 0
	v_mfma_f32_16x16x16_bf16 v[108:111], v[52:53], v[54:55], 0
	s_nop 7
	v_cvt_pk_bf16_f32 v62, v108, v109
	v_cvt_pk_bf16_f32 v63, v110, v111
	s_waitcnt lgkmcnt(0)
	s_nop 0
	v_mfma_f32_16x16x32_bf16 v[112:115], v[56:59], v[60:63], v[112:115]
	v_mfma_f32_16x16x32_bf16 v[8:11], v[88:91], v[60:63], v[8:11]
	v_mfma_f32_16x16x32_bf16 v[16:19], v[92:95], v[60:63], v[16:19]
	v_mfma_f32_16x16x32_bf16 v[20:23], v[96:99], v[60:63], v[20:23]
	v_mfma_f32_16x16x32_bf16 v[24:27], v[100:103], v[60:63], v[24:27]
	ds_read_b128 v[64:67], v161 offset:0
	ds_read_b128 v[68:71], v161 offset:16
	ds_read_b128 v[72:75], v161 offset:128
	ds_read_b128 v[84:87], v161 offset:144
	v_cvt_pk_bf16_f32 v167, v112, v112
	ds_read_b64 v[60:61], v160 offset:21760
	global_store_short v166, v167, s[48:49] offset:0
	v_cvt_pk_bf16_f32 v167, v113, v113
	global_store_short v166, v167, s[48:49] offset:1024
	v_cvt_pk_bf16_f32 v167, v114, v114
	global_store_short v166, v167, s[48:49] offset:2048
	v_cvt_pk_bf16_f32 v167, v115, v115
	global_store_short v166, v167, s[48:49] offset:3072
	s_waitcnt lgkmcnt(1)
	s_add_u32 s58, s58, 1
	s_add_u32 s48, s48, 0x4000
	s_addc_u32 s49, s49, 0
	v_pk_mul_f32 v[8:9], v[8:9], v[64:65]
	v_pk_mul_f32 v[10:11], v[10:11], v[66:67]
	v_pk_mul_f32 v[16:17], v[16:17], v[68:69]
	v_pk_mul_f32 v[18:19], v[18:19], v[70:71]
	v_pk_mul_f32 v[20:21], v[20:21], v[72:73]
	v_pk_mul_f32 v[22:23], v[22:23], v[74:75]
	v_pk_mul_f32 v[24:25], v[24:25], v[84:85]
	v_pk_mul_f32 v[26:27], v[26:27], v[86:87]
	s_add_u32 s57, s57, 11520
	s_cmp_ge_u32 s58, 256
	s_cbranch_scc1 .Lsc_c_itend
; __device__ __forceinline__ void phase_scan2(const Params& p, int l, LAS unsigned char* lds) {
;     ...
;         auto consume = [&](int c, LAS const unsigned char* sl) {
;             const bf16x8 s0 = __builtin_bit_cast(bf16x8, (u32x4){pk_bf16(ST[0][0], ST[0][1]), pk_bf16(ST[0][2], ST[0][3]), pk_bf16(ST[1][0], ST[1][1]), pk_bf16(ST[1][2], ST[1][3])});
;             const bf16x8 s1 = __builtin_bit_cast(bf16x8, (u32x4){pk_bf16(ST[2][0], ST[2][1]), pk_bf16(ST[2][2], ST[2][3]), pk_bf16(ST[3][0], ST[3][1]), pk_bf16(ST[3][2], ST[3][3])});
;             const bf16x8 at0 = *(LAS const bf16x8*)(sl + SC_AT + (fr * 32 + fq * 8) * 2), at1 = *(LAS const bf16x8*)(sl + SC_AT + ((16 + fr) * 32 + fq * 8) * 2);
;             const bf16x8 rt0 = *(LAS const bf16x8*)(sl + SC_RT + (fr * 32 + fq * 8) * 2), rt1 = *(LAS const bf16x8*)(sl + SC_RT + ((16 + fr) * 32 + fq * 8) * 2);
;             const int mo = (fr * 16 + 4 * fq) * 2;
;             const bf16x8 vf = frag4(sl + SC_VP + mo), akf = frag4(sl + SC_AK + mo), xf = frag4(sl + SC_X + mo), rbf = frag4(sl + SC_RB + mo), rkf = frag4(sl + SC_RK + mo);
;             const f32x4 z = (f32x4){0.f, 0.f, 0.f, 0.f};
;             f32x4 g = __builtin_amdgcn_mfma_f32_16x16x32_bf16(at0, s0, z, 0, 0, 0);
;             g = __builtin_amdgcn_mfma_f32_16x16x32_bf16(at1, s1, g, 0, 0, 0);
;             g = __builtin_amdgcn_mfma_f32_16x16x32_bf16(akf, vf, g, 0, 0, 0);
;             const f32x4 sa = __builtin_amdgcn_mfma_f32_16x16x32_bf16(xf, cfrag(g), z, 0, 0, 0);
;             const bf16x8 saf = cfrag(sa);
;             f32x4 y = __builtin_amdgcn_mfma_f32_16x16x32_bf16(rt0, s0, z, 0, 0, 0);
;             y = __builtin_amdgcn_mfma_f32_16x16x32_bf16(rt1, s1, y, 0, 0, 0);
;             y = __builtin_amdgcn_mfma_f32_16x16x32_bf16(rbf, saf, y, 0, 0, 0);
;             y = __builtin_amdgcn_mfma_f32_16x16x32_bf16(rkf, vf, y, 0, 0, 0);
; #pragma unroll
;             for (int jt = 0; jt < 4; ++jt) {
;                 const f32x4 wc = *(LAS const f32x4*)(sl + SC_WC + (16 * jt + 4 * fq) * 4);
;                 const bf16x8 bb = frag4(sl + SC_BBT + ((16 * jt + fr) * SC_BS + 4 * fq) * 2), kb = frag4(sl + SC_KBT + ((16 * jt + fr) * SC_BS + 4 * fq) * 2);
;                 f32x4 acc = ST[jt];
;                 acc = __builtin_amdgcn_mfma_f32_16x16x32_bf16(bb, saf, acc, 0, 0, 0);
;                 acc = __builtin_amdgcn_mfma_f32_16x16x32_bf16(kb, vf, acc, 0, 0, 0);
	v_add_u32_e32 v168, s57, v7
	v_add_u32_e32 v162, s57, v165
	ds_read_b64_tr_b16 v[14:15], v168 offset:8192
	ds_read_b64_tr_b16 v[52:53], v168 offset:8704
	ds_read_b64_tr_b16 v[56:57], v168 offset:9728
	ds_read_b64_tr_b16 v[58:59], v168 offset:9216
	v_add_u32_e32 v172, s57, v170
	ds_read_b64_tr_b16 v[88:89], v162 offset:2048
	ds_read_b64_tr_b16 v[92:93], v162 offset:2056
	v_add_u32_e32 v82, s57, v163
	v_add_u32_e32 v160, s57, v13
	v_add_u32_e32 v161, s57, v164
	v_add_u32_e32 v171, s57, v169
	ds_read_b64_tr_b16 v[96:97], v172 offset:2048
	v_cvt_pk_bf16_f32 v28, v8, v9
	v_cvt_pk_bf16_f32 v29, v10, v11
	v_cvt_pk_bf16_f32 v30, v16, v17
	v_cvt_pk_bf16_f32 v31, v18, v19
	v_cvt_pk_bf16_f32 v32, v20, v21
	v_cvt_pk_bf16_f32 v33, v22, v23
	v_cvt_pk_bf16_f32 v34, v24, v25
	v_cvt_pk_bf16_f32 v35, v26, v27
	ds_read_b64_tr_b16 v[100:101], v172 offset:2056
	s_waitcnt lgkmcnt(12)
	v_mfma_f32_16x16x32_bf16 v[104:107], v[36:39], v[28:31], 0
	ds_read_b128 v[36:39], v82 offset:11520
	s_waitcnt lgkmcnt(12)
	v_mfma_f32_16x16x32_bf16 v[112:115], v[44:47], v[28:31], 0
	ds_read_b128 v[44:47], v82 offset:13568
	s_waitcnt lgkmcnt(12)
	v_mfma_f32_16x16x32_bf16 v[104:107], v[40:43], v[32:35], v[104:107]
	ds_read_b128 v[40:43], v171 offset:11520
	s_waitcnt lgkmcnt(12)
	v_mfma_f32_16x16x32_bf16 v[112:115], v[48:51], v[32:35], v[112:115]
	ds_read_b128 v[48:51], v171 offset:13568
	s_waitcnt lgkmcnt(11)
	s_nop 0
	v_mfma_f32_16x16x16_bf16 v[104:107], v[14:15], v[60:61], v[104:107]
	ds_read_b64_tr_b16 v[90:91], v162 offset:0
	ds_read_b64_tr_b16 v[94:95], v162 offset:8
	ds_read_b64_tr_b16 v[98:99], v172 offset:0
	ds_read_b64_tr_b16 v[102:103], v172 offset:8
	s_nop 3
	v_cvt_pk_bf16_f32 v54, v104, v105
	v_cvt_pk_bf16_f32 v55, v106, v107
	s_waitcnt lgkmcnt(14)
	s_nop 0
	v_mfma_f32_16x16x16_bf16 v[108:111], v[52:53], v[54:55], 0
	s_nop 7
	v_cvt_pk_bf16_f32 v62, v108, v109
	v_cvt_pk_bf16_f32 v63, v110, v111
	s_waitcnt lgkmcnt(0)
	s_nop 0
	v_mfma_f32_16x16x32_bf16 v[112:115], v[56:59], v[60:63], v[112:115]
	v_mfma_f32_16x16x32_bf16 v[8:11], v[88:91], v[60:63], v[8:11]
	v_mfma_f32_16x16x32_bf16 v[16:19], v[92:95], v[60:63], v[16:19]
	v_mfma_f32_16x16x32_bf16 v[20:23], v[96:99], v[60:63], v[20:23]
	v_mfma_f32_16x16x32_bf16 v[24:27], v[100:103], v[60:63], v[24:27]
	ds_read_b128 v[64:67], v161 offset:0
	ds_read_b128 v[68:71], v161 offset:16
	ds_read_b128 v[72:75], v161 offset:128
	ds_read_b128 v[84:87], v161 offset:144
	v_cvt_pk_bf16_f32 v167, v112, v112
	ds_read_b64 v[60:61], v160 offset:21760
	global_store_short v166, v167, s[48:49] offset:0
	v_cvt_pk_bf16_f32 v167, v113, v113
	global_store_short v166, v167, s[48:49] offset:1024
	v_cvt_pk_bf16_f32 v167, v114, v114
	global_store_short v166, v167, s[48:49] offset:2048
	v_cvt_pk_bf16_f32 v167, v115, v115
	global_store_short v166, v167, s[48:49] offset:3072
	s_waitcnt lgkmcnt(1)
	s_add_u32 s58, s58, 1
	s_add_u32 s48, s48, 0x4000
	s_addc_u32 s49, s49, 0
	v_pk_mul_f32 v[8:9], v[8:9], v[64:65]
	v_pk_mul_f32 v[10:11], v[10:11], v[66:67]
	v_pk_mul_f32 v[16:17], v[16:17], v[68:69]
	v_pk_mul_f32 v[18:19], v[18:19], v[70:71]
	v_pk_mul_f32 v[20:21], v[20:21], v[72:73]
	v_pk_mul_f32 v[22:23], v[22:23], v[74:75]
	v_pk_mul_f32 v[24:25], v[24:25], v[84:85]
	v_pk_mul_f32 v[26:27], v[26:27], v[86:87]
	s_add_u32 s57, s57, 11520
	s_cmp_ge_u32 s58, 256
	s_cbranch_scc1 .Lsc_c_itend
	v_add_u32_e32 v168, s57, v7
	v_add_u32_e32 v162, s57, v165
	ds_read_b64_tr_b16 v[14:15], v168 offset:8192
	ds_read_b64_tr_b16 v[52:53], v168 offset:8704
	ds_read_b64_tr_b16 v[56:57], v168 offset:9728
	ds_read_b64_tr_b16 v[58:59], v168 offset:9216
	v_add_u32_e32 v172, s57, v170
	ds_read_b64_tr_b16 v[88:89], v162 offset:2048
	ds_read_b64_tr_b16 v[92:93], v162 offset:2056
	v_add_u32_e32 v82, s57, v163
	v_add_u32_e32 v160, s57, v13
	v_add_u32_e32 v161, s57, v164
	v_add_u32_e32 v171, s57, v169
	ds_read_b64_tr_b16 v[96:97], v172 offset:2048
	v_cvt_pk_bf16_f32 v28, v8, v9
	v_cvt_pk_bf16_f32 v29, v10, v11
	v_cvt_pk_bf16_f32 v30, v16, v17
	v_cvt_pk_bf16_f32 v31, v18, v19
	v_cvt_pk_bf16_f32 v32, v20, v21
	v_cvt_pk_bf16_f32 v33, v22, v23
	v_cvt_pk_bf16_f32 v34, v24, v25
	v_cvt_pk_bf16_f32 v35, v26, v27
	ds_read_b64_tr_b16 v[100:101], v172 offset:2056
	s_waitcnt lgkmcnt(12)
	v_mfma_f32_16x16x32_bf16 v[104:107], v[36:39], v[28:31], 0
	s_waitcnt lgkmcnt(11)
	v_mfma_f32_16x16x32_bf16 v[112:115], v[44:47], v[28:31], 0
	s_waitcnt lgkmcnt(10)
	v_mfma_f32_16x16x32_bf16 v[104:107], v[40:43], v[32:35], v[104:107]
	s_waitcnt lgkmcnt(9)
	v_mfma_f32_16x16x32_bf16 v[112:115], v[48:51], v[32:35], v[112:115]
	s_waitcnt lgkmcnt(7)
	s_nop 2
	v_mfma_f32_16x16x16_bf16 v[104:107], v[14:15], v[60:61], v[104:107]
	ds_read_b64_tr_b16 v[90:91], v162 offset:0
	ds_read_b64_tr_b16 v[94:95], v162 offset:8
	ds_read_b64_tr_b16 v[98:99], v172 offset:0
	ds_read_b64_tr_b16 v[102:103], v172 offset:8
	s_nop 3
	v_cvt_pk_bf16_f32 v54, v104, v105
	v_cvt_pk_bf16_f32 v55, v106, v107
	s_waitcnt lgkmcnt(10)
	s_nop 0
	v_mfma_f32_16x16x16_bf16 v[108:111], v[52:53], v[54:55], 0
	s_nop 7
	v_cvt_pk_bf16_f32 v62, v108, v109
	v_cvt_pk_bf16_f32 v63, v110, v111
	s_waitcnt lgkmcnt(0)
	s_nop 0
	v_mfma_f32_16x16x32_bf16 v[112:115], v[56:59], v[60:63], v[112:115]
	ds_read_b128 v[64:67], v161 offset:0
	ds_read_b128 v[68:71], v161 offset:16
	ds_read_b128 v[72:75], v161 offset:128
	ds_read_b128 v[84:87], v161 offset:144
	v_mfma_f32_16x16x32_bf16 v[8:11], v[88:91], v[60:63], v[8:11]
	v_mfma_f32_16x16x32_bf16 v[16:19], v[92:95], v[60:63], v[16:19]
	v_mfma_f32_16x16x32_bf16 v[20:23], v[96:99], v[60:63], v[20:23]
	v_mfma_f32_16x16x32_bf16 v[24:27], v[100:103], v[60:63], v[24:27]
	v_cvt_pk_bf16_f32 v167, v112, v112
	global_store_short v166, v167, s[48:49] offset:0
	v_cvt_pk_bf16_f32 v167, v113, v113
	global_store_short v166, v167, s[48:49] offset:1024
	v_cvt_pk_bf16_f32 v167, v114, v114
	global_store_short v166, v167, s[48:49] offset:2048
	v_cvt_pk_bf16_f32 v167, v115, v115
	global_store_short v166, v167, s[48:49] offset:3072
	s_waitcnt lgkmcnt(0)
	s_add_u32 s58, s58, 1
	s_add_u32 s48, s48, 0x4000
	v_pk_mul_f32 v[8:9], v[8:9], v[64:65]
	v_pk_mul_f32 v[10:11], v[10:11], v[66:67]
	v_pk_mul_f32 v[16:17], v[16:17], v[68:69]
	v_pk_mul_f32 v[18:19], v[18:19], v[70:71]
	v_pk_mul_f32 v[20:21], v[20:21], v[72:73]
	v_pk_mul_f32 v[22:23], v[22:23], v[74:75]
	v_pk_mul_f32 v[24:25], v[24:25], v[84:85]
	v_pk_mul_f32 v[26:27], v[26:27], v[86:87]
	s_addc_u32 s49, s49, 0
	s_add_u32 s57, s57, 11520

; #define LAS __attribute__((address_space(3)))
; __device__ __forceinline__ int otid() { int t = threadIdx.x; asm volatile("" : "+v"(t)); return t; }
; __device__ __forceinline__ int obid() { int b = blockIdx.x; asm volatile("" : "+s"(b)); return b; }
; __device__ __forceinline__ void phase_attn(const Params& p, int l, LAS unsigned char* ldsb) {
;     ...
;     const float* relb = p.in[7]; const float* sinks = p.in[8] + l * 8;
;     const int tid = otid(), wid = tid >> 6, lane = tid & 63, fr = lane & 15, fq = lane >> 4;
;     LAS bf16_t* Ks = (LAS bf16_t*)ldsb;
;     LAS bf16_t* Vt = (LAS bf16_t*)(ldsb + 36864);
;     LAS float* biasL = (LAS float*)(ldsb + 70656);
;     LAS bf16_t* Pw = (LAS bf16_t*)(ldsb + 72704) + wid * (16 * 168);
;     for (int item = obid(); item < 512; item += gridDim.x) {
;         const int g = item & 1, n = (item >> 1) & 31, b = item >> 6;
;         const long tokc = (long)b * SEQ + n * 128, tokp = tokc - 128;
;         for (int idx = tid; idx < 2048; idx += 512) {
;             const int key = idx >> 3, d8 = idx & 7; u32x4 v = (u32x4){0u, 0u, 0u, 0u}, kv = (u32x4){0u, 0u, 0u, 0u};
;             if (n > 0 || key >= 128) { const bf16_t* src = QKV + (size_t)(tokp + key) * 768 + 512 + g * 64 + d8 * 8; kv = *(const u32x4*)src; v = *(const u32x4*)(src + 128); }
;             *(LAS u32x4*)(Ks + key * 72 + d8 * 8) = kv;
; #pragma unroll
;             for (int e = 0; e < 8; ++e) Vt[(d8 * 8 + e) * 264 + key] = (bf16_t)((e & 1) ? (v[e >> 1] >> 16) : (v[e >> 1] & 0xffffu));
;         }
;         { const int hl = tid >> 7, d = tid & 127; int bk = d;
;           if (d >= 16) { bk = 16 + (int)(__logf((float)d * 0.0625f) * (16.f / 2.07944154168f)); bk = bk > 31 ? 31 : bk; }
;           biasL[tid] = relb[bk * 8 + g * 4 + hl]; }
;         __syncthreads();
;         const int hl = wid >> 1, hq = g * 4 + hl; const float sink = sinks[hq];
.Lat_entry:
	s_cmp_lt_u32 s5, 128
	s_cbranch_scc1 .Lat_end
	v_and_b32_e32 v0, 63, v183
	v_and_b32_e32 v1, 15, v183
	v_bfe_u32 v2, v183, 4, 2
	v_lshrrev_b32_e32 v4, 6, v183
	s_nop 0
	v_readfirstlane_b32 s44, v4
	s_nop 0
	s_lshr_b32 s45, s44, 1
	s_and_b32 s46, s44, 1
	v_readlane_b32 s0, v252, 0
	v_readlane_b32 s1, v252, 1
	s_sub_u32 s0, s0, 0xe0
	s_subb_u32 s1, s1, 0
	s_load_dwordx2 s[14:15], s[0:1], 0x38
	s_load_dwordx2 s[26:27], s[0:1], 0x40
	v_readlane_b32 s85, v243, 45
	s_nop 0
	s_lshr_b32 s85, s85, 1
	s_mov_b32 s82, 0x3e38aa3b
	v_lshrrev_b32_e32 v4, 3, v183
	v_and_b32_e32 v5, 7, v183
	v_mul_u32_u24_e32 v7, 1536, v4
	v_lshl_add_u32 v7, v5, 4, v7
	v_and_b32_e32 v6, 7, v4
	v_xor_b32_e32 v6, v6, v5
	v_lshlrev_b32_e32 v6, 4, v6
	v_lshl_add_u32 v6, v4, 7, v6
	v_bfe_u32 v3, v4, 1, 3
	v_xor_b32_e32 v3, v3, v5
	v_lshlrev_b32_e32 v3, 4, v3
	v_lshl_add_u32 v3, v4, 7, v3
	v_and_b32_e32 v8, 127, v183
	v_lshrrev_b32_e32 v4, 7, v183
	v_cvt_f32_u32_e32 v5, v8
	v_mul_f32_e32 v5, 0x3d800000, v5
	v_max_f32_e32 v5, 1.0, v5
	v_log_f32_e32 v5, v5
	s_nop 0
	v_mul_f32_e32 v5, 0x40aaaaab, v5
	v_cvt_i32_f32_e32 v5, v5
	v_add_u32_e32 v5, 16, v5
	v_min_u32_e32 v5, 31, v5
	v_cmp_gt_u32_e32 vcc, 16, v8
	s_nop 1
	v_cndmask_b32_e32 v10, v5, v8, vcc
	v_lshlrev_b32_e32 v10, 5, v10
	v_lshl_add_u32 v10, v4, 2, v10
	v_mul_u32_u24_e32 v9, 3328, v4
	v_sub_u32_e32 v5, 160, v8
	v_lshl_add_u32 v9, v5, 2, v9
	v_add_u32_e32 v9, 131072, v9
	v_add_u32_e32 v5, 96, v8
	v_subrev_u32_e32 v29, 32, v8
	v_cmp_gt_u32_e32 vcc, 32, v8
	s_nop 1
	v_cndmask_b32_e32 v5, v5, v29, vcc
	v_sub_u32_e32 v5, 160, v5
	v_mul_u32_u24_e32 v11, 3328, v4
	v_lshl_add_u32 v11, v5, 2, v11
	v_add_u32_e32 v11, 131072, v11
	v_lshlrev_b32_e32 v5, 2, v183
	v_add_u32_e32 v5, 144384, v5
	v_cmp_gt_u32_e32 vcc, 65, v8
	s_nop 1
	v_cndmask_b32_e32 v11, v5, v11, vcc
	v_bfe_u32 v4, v1, 1, 3
	v_xor_b32_e32 v4, v4, v2
	v_lshlrev_b32_e32 v4, 4, v4
	v_lshl_add_u32 v13, v1, 7, v4
	v_xor_b32_e32 v14, 64, v13
	v_and_b32_e32 v4, 3, v1
	v_mul_u32_u24_e32 v17, 832, v4
	v_and_b32_e32 v4, 12, v1
	v_lshlrev_b32_e32 v4, 2, v4
	v_sub_u32_e32 v17, v17, v4
	v_lshl_add_u32 v17, v2, 4, v17
	s_mul_i32 s51, s45, 3328
	s_add_u32 s51, s51, 131072
	v_add_u32_e32 v17, s51, v17
	v_lshrrev_b32_e32 v4, 2, v1
	v_lshl_add_u32 v4, v2, 2, v4
	v_and_b32_e32 v5, 7, v4
	v_bfe_u32 v29, v1, 1, 1
	v_and_b32_e32 v30, 1, v1
	v_lshlrev_b32_e32 v30, 3, v30
	v_lshl_add_u32 v30, v4, 7, v30
	v_add_u32_e32 v30, 32768, v30
	v_or_b32_e32 v4, 0, v29
	v_xor_b32_e32 v4, v4, v5
	v_lshl_add_u32 v19, v4, 4, v30
	v_or_b32_e32 v4, 2, v29
	v_xor_b32_e32 v4, v4, v5
	v_lshl_add_u32 v20, v4, 4, v30
	v_or_b32_e32 v4, 4, v29
	v_xor_b32_e32 v4, v4, v5
	v_lshl_add_u32 v21, v4, 4, v30
	v_or_b32_e32 v4, 6, v29
	v_xor_b32_e32 v4, v4, v5
	v_lshl_add_u32 v22, v4, 4, v30
	v_mul_u32_u24_e32 v27, 1536, v1
	v_lshl_add_u32 v27, v2, 4, v27
	v_lshlrev_b32_e32 v28, 10, v1
	v_lshl_add_u32 v28, v2, 3, v28
	v_xor_b32_e32 v29, 16, v0
	v_lshlrev_b32_e32 v29, 2, v29
	v_xor_b32_e32 v30, 32, v0
	v_lshlrev_b32_e32 v30, 2, v30
	s_sub_u32 s25, s5, 128
	s_and_b32 s2, s25, 1
	s_lshr_b32 s13, s25, 1
	s_and_b32 s13, s13, 31
	s_lshr_b32 s25, s25, 6
	s_lshl_b32 s32, s25, 12
	s_lshl_b32 s51, s13, 7
	s_add_u32 s32, s32, s51
	s_lshl_b32 s47, s2, 2
	s_add_u32 s47, s47, s45
	s_waitcnt lgkmcnt(0)
	s_sleep 127
	s_sleep 127
	s_sleep 127
	s_sleep 127
	s_sleep 127
	s_sleep 127
	s_sleep 127
	s_sleep 127
	s_mov_b32 s87, 0

; #define LAS __attribute__((address_space(3)))
; __device__ __forceinline__ void phase_attn(const Params& p, int l, LAS unsigned char* ldsb) {
;     ...
;         for (int rt = 0; rt < 4; ++rt) {
;             const int q0 = (wid & 1) * 64 + rt * 16, kstart = q0 < 96 ? q0 : 96;
;             bf16x8 qa0, qa1; { const bf16_t* qp = QKV + (size_t)(tokc + q0 + fr) * 768 + hq * 64 + fq * 8; qa0 = *(const bf16x8*)qp; qa1 = *(const bf16x8*)(qp + 32); }
;             f32x4 S[10];
; #pragma unroll
;             for (int kt = 0; kt < 10; ++kt) {
;                 LAS const bf16_t* kp = Ks + (kstart + kt * 16 + fr) * 72 + fq * 8;
;                 const bf16x8 k0 = *(LAS const bf16x8*)kp, k1 = *(LAS const bf16x8*)(kp + 32);
;                 f32x4 z = (f32x4){0.f, 0.f, 0.f, 0.f};
;                 z = __builtin_amdgcn_mfma_f32_16x16x32_bf16(qa0, k0, z, 0, 0, 0);
;                 z = __builtin_amdgcn_mfma_f32_16x16x32_bf16(qa1, k1, z, 0, 0, 0);
;                 S[kt] = z;
;             }
;             float mx[4] = {-INFINITY, -INFINITY, -INFINITY, -INFINITY};
; #pragma unroll
;             for (int kt = 0; kt < 10; ++kt)
; #pragma unroll
;                 for (int j = 0; j < 4; ++j) {
;                     const int key = kstart + kt * 16 + fr, dist = q0 + 4 * fq + j + 128 - key;
;                     const bool ok = (dist >= 0) && (dist < 128) && (n > 0 || key >= 128);
;                     const float s = ok ? (S[kt][j] * 0.125f + biasL[hl * 128 + (dist & 127)]) : -INFINITY;
;                     S[kt][j] = s; mx[j] = fmaxf(mx[j], s);
;                 }
.Lat_rt:
	s_and_b32 s51, s48, 3
	s_lshl_b32 s51, s51, 4
	s_lshl_b32 s49, s46, 6
	s_add_u32 s49, s49, s51
	s_min_u32 s50, s49, 96
	s_lshr_b32 s51, s48, 2
	s_lshl_b32 s81, s51, 13
	s_add_u32 s81, s81, s32
	s_add_u32 s81, s81, s49
	s_lshl_b32 s81, s81, 10
	s_lshl_b32 s84, s47, 7
	s_add_u32 s81, s81, s84
	s_add_u32 s81, s81, 0x7000000
	s_add_u32 s42, s74, s81
	s_addc_u32 s43, s75, 0
	s_lshl_b32 s51, s51, 16
	s_lshl_b32 s81, s50, 7
	s_add_u32 s51, s51, s81
	v_add_u32_e32 v15, s51, v13
	v_add_u32_e32 v16, s51, v14
	v_add_u32_e32 v23, s51, v19
	v_add_u32_e32 v24, s51, v20
	v_add_u32_e32 v25, s51, v21
	v_add_u32_e32 v26, s51, v22
	s_sub_u32 s81, s49, s50
	s_sub_u32 s81, 32, s81
	s_lshl_b32 s81, s81, 2
	v_add_u32_e32 v18, s81, v17
	s_sub_u32 s84, 128, s50
	s_lshr_b32 s84, s84, 4
	s_cmp_eq_u32 s13, 0
	s_cselect_b32 s84, s84, 0
	ds_read_b128 v[104:107], v18 offset:0
	ds_read_b128 v[108:111], v18 offset:64
	ds_read_b128 v[112:115], v18 offset:128
	ds_read_b128 v[116:119], v18 offset:192
	ds_read_b128 v[120:123], v18 offset:256
	ds_read_b128 v[124:127], v18 offset:320
	ds_read_b128 v[128:131], v18 offset:384
	ds_read_b128 v[132:135], v18 offset:448
	ds_read_b128 v[136:139], v18 offset:512
	ds_read_b128 v[140:143], v18 offset:576
	ds_read_b128 v[48:51], v15 offset:0
	ds_read_b128 v[52:55], v16 offset:0
	ds_read_b128 v[56:59], v15 offset:2048
	ds_read_b128 v[60:63], v16 offset:2048
	s_waitcnt lgkmcnt(2)
	v_mfma_f32_16x16x32_bf16 v[64:67], v[48:51], v[40:43], 0
	v_mfma_f32_16x16x32_bf16 v[64:67], v[52:55], v[44:47], v[64:67]
	ds_read_b128 v[48:51], v15 offset:4096
	ds_read_b128 v[52:55], v16 offset:4096
	s_waitcnt lgkmcnt(2)
	v_mfma_f32_16x16x32_bf16 v[68:71], v[56:59], v[40:43], 0
	v_mfma_f32_16x16x32_bf16 v[68:71], v[60:63], v[44:47], v[68:71]
	ds_read_b128 v[56:59], v15 offset:6144
	ds_read_b128 v[60:63], v16 offset:6144
	s_waitcnt lgkmcnt(2)
	v_mfma_f32_16x16x32_bf16 v[72:75], v[48:51], v[40:43], 0
	v_mfma_f32_16x16x32_bf16 v[72:75], v[52:55], v[44:47], v[72:75]
	ds_read_b128 v[48:51], v15 offset:8192
	ds_read_b128 v[52:55], v16 offset:8192
	s_waitcnt lgkmcnt(2)
	v_mfma_f32_16x16x32_bf16 v[76:79], v[56:59], v[40:43], 0
	v_mfma_f32_16x16x32_bf16 v[76:79], v[60:63], v[44:47], v[76:79]
	ds_read_b128 v[56:59], v15 offset:10240
	ds_read_b128 v[60:63], v16 offset:10240
	s_waitcnt lgkmcnt(2)
	v_mfma_f32_16x16x32_bf16 v[80:83], v[48:51], v[40:43], 0
	v_mfma_f32_16x16x32_bf16 v[80:83], v[52:55], v[44:47], v[80:83]
	ds_read_b128 v[48:51], v15 offset:12288
	ds_read_b128 v[52:55], v16 offset:12288
	s_waitcnt lgkmcnt(2)
	v_mfma_f32_16x16x32_bf16 v[84:87], v[56:59], v[40:43], 0
	v_mfma_f32_16x16x32_bf16 v[84:87], v[60:63], v[44:47], v[84:87]
	ds_read_b128 v[56:59], v15 offset:14336
	ds_read_b128 v[60:63], v16 offset:14336
	s_waitcnt lgkmcnt(2)
	v_mfma_f32_16x16x32_bf16 v[88:91], v[48:51], v[40:43], 0
	v_mfma_f32_16x16x32_bf16 v[88:91], v[52:55], v[44:47], v[88:91]
	ds_read_b128 v[48:51], v15 offset:16384
	ds_read_b128 v[52:55], v16 offset:16384
	s_waitcnt lgkmcnt(2)
	v_mfma_f32_16x16x32_bf16 v[92:95], v[56:59], v[40:43], 0
	v_mfma_f32_16x16x32_bf16 v[92:95], v[60:63], v[44:47], v[92:95]
	ds_read_b128 v[56:59], v15 offset:18432
	ds_read_b128 v[60:63], v16 offset:18432
	s_waitcnt lgkmcnt(2)
	v_mfma_f32_16x16x32_bf16 v[96:99], v[48:51], v[40:43], 0
	v_mfma_f32_16x16x32_bf16 v[96:99], v[52:55], v[44:47], v[96:99]
	s_waitcnt lgkmcnt(0)
	v_mfma_f32_16x16x32_bf16 v[100:103], v[56:59], v[40:43], 0
	v_mfma_f32_16x16x32_bf16 v[100:103], v[60:63], v[44:47], v[100:103]
	s_add_u32 s51, s48, 1
	s_min_u32 s51, s51, 7
	s_lshr_b32 s81, s51, 2
	s_lshl_b32 s81, s81, 13
	s_and_b32 s51, s51, 3
	s_lshl_b32 s51, s51, 4
	s_add_u32 s81, s81, s51
	s_lshl_b32 s51, s46, 6
	s_add_u32 s81, s81, s51
	s_add_u32 s81, s81, s32
	s_mul_i32 s81, s81, 1536
	s_lshl_b32 s51, s47, 7
	s_add_u32 s81, s81, s51
	s_add_u32 s40, s74, s81
	s_addc_u32 s41, s75, 0
	global_load_dwordx4 v[40:43], v27, s[40:41]
	global_load_dwordx4 v[44:47], v27, s[40:41] offset:64
	v_fma_f32 v64, v64, s82, v104
	v_fma_f32 v65, v65, s82, v105
	v_fma_f32 v66, v66, s82, v106
	v_fma_f32 v67, v67, s82, v107
	v_fma_f32 v68, v68, s82, v108
	v_fma_f32 v69, v69, s82, v109
	v_fma_f32 v70, v70, s82, v110
	v_fma_f32 v71, v71, s82, v111
	v_fma_f32 v72, v72, s82, v112
	v_fma_f32 v73, v73, s82, v113
	v_fma_f32 v74, v74, s82, v114
	v_fma_f32 v75, v75, s82, v115
	v_fma_f32 v76, v76, s82, v116
	v_fma_f32 v77, v77, s82, v117
	v_fma_f32 v78, v78, s82, v118
	v_fma_f32 v79, v79, s82, v119
	v_fma_f32 v80, v80, s82, v120
	v_fma_f32 v81, v81, s82, v121
	v_fma_f32 v82, v82, s82, v122
	v_fma_f32 v83, v83, s82, v123
	v_fma_f32 v84, v84, s82, v124
	v_fma_f32 v85, v85, s82, v125
	v_fma_f32 v86, v86, s82, v126
	v_fma_f32 v87, v87, s82, v127
	v_fma_f32 v88, v88, s82, v128
	v_fma_f32 v89, v89, s82, v129
	v_fma_f32 v90, v90, s82, v130
	v_fma_f32 v91, v91, s82, v131
	v_fma_f32 v92, v92, s82, v132
	v_fma_f32 v93, v93, s82, v133
	v_fma_f32 v94, v94, s82, v134
	v_fma_f32 v95, v95, s82, v135
	v_fma_f32 v96, v96, s82, v136
	v_fma_f32 v97, v97, s82, v137
	v_fma_f32 v98, v98, s82, v138
	v_fma_f32 v99, v99, s82, v139
	v_fma_f32 v100, v100, s82, v140
	v_fma_f32 v101, v101, s82, v141
	v_fma_f32 v102, v102, s82, v142
	v_fma_f32 v103, v103, s82, v143
	s_cmp_eq_u32 s84, 0
	s_nop 0
	s_cbranch_scc1 .Lat_nomask
	s_cmp_gt_u32 s84, 0
	s_cselect_b32 s86, 0xff800000, 0
	v_add_f32_e32 v64, s86, v64
	v_add_f32_e32 v65, s86, v65
	v_add_f32_e32 v66, s86, v66
	v_add_f32_e32 v67, s86, v67
	s_cmp_gt_u32 s84, 1
	s_cselect_b32 s86, 0xff800000, 0
	v_add_f32_e32 v68, s86, v68
	v_add_f32_e32 v69, s86, v69
	v_add_f32_e32 v70, s86, v70
	v_add_f32_e32 v71, s86, v71
	s_cmp_gt_u32 s84, 2
	s_cselect_b32 s86, 0xff800000, 0
	v_add_f32_e32 v72, s86, v72
	v_add_f32_e32 v73, s86, v73
	v_add_f32_e32 v74, s86, v74
	v_add_f32_e32 v75, s86, v75
	s_cmp_gt_u32 s84, 3
	s_cselect_b32 s86, 0xff800000, 0
	v_add_f32_e32 v76, s86, v76
	v_add_f32_e32 v77, s86, v77
	v_add_f32_e32 v78, s86, v78
	v_add_f32_e32 v79, s86, v79
	s_cmp_gt_u32 s84, 4
	s_cselect_b32 s86, 0xff800000, 0
	v_add_f32_e32 v80, s86, v80
	v_add_f32_e32 v81, s86, v81
	v_add_f32_e32 v82, s86, v82
	v_add_f32_e32 v83, s86, v83
	s_cmp_gt_u32 s84, 5
	s_cselect_b32 s86, 0xff800000, 0
	v_add_f32_e32 v84, s86, v84
	v_add_f32_e32 v85, s86, v85
	v_add_f32_e32 v86, s86, v86
	v_add_f32_e32 v87, s86, v87
	s_cmp_gt_u32 s84, 6
	s_cselect_b32 s86, 0xff800000, 0
	v_add_f32_e32 v88, s86, v88
	v_add_f32_e32 v89, s86, v89
	v_add_f32_e32 v90, s86, v90
	v_add_f32_e32 v91, s86, v91
	s_cmp_gt_u32 s84, 7
	s_cselect_b32 s86, 0xff800000, 0
	v_add_f32_e32 v92, s86, v92
	v_add_f32_e32 v93, s86, v93
	v_add_f32_e32 v94, s86, v94
	v_add_f32_e32 v95, s86, v95
	s_nop 1
